# K tile by LDS-DMA only (V still register-staged), for comparison with K+V DMA
# speedup vs baseline: 1.0781x; 1.0162x over previous
; template <int MODE, bool FROZEN = false>
; __device__ __forceinline__ bool attn_unit(LAS unsigned char* lds, const Params& p, int l, int ua, int ub) {
;     ...
;         const float s1 = wave_sum(lq[lane] * lq[64 + lane]), s2 = wave_sum(lq[128 + lane] * lq[192 + lane]);
;         lam_init = 0.8f - 0.6f * expf(-0.3f * (float)l);
;         lam = expf(s1) - expf(s2) + lam_init;
;     ...
;     for (int i = 0; i < NKC; ++i) { const int cid = tid + 512 * i, row = cid / KCH, ch = cid % KCH; ksrc[i] = (unsigned)(row * NPROJ + kcol + ch * 8); kdst[i] = OFF_K + row * KPB + ch * 16; }
; #pragma unroll
;     for (int i = 0; i < NVC; ++i) { const int cid = tid + 512 * i, row = cid >> 3, ch = cid & 7; vsrc[i] = (unsigned)((vcol + row) * S + ch * 8); vdst[i] = OFF_V + row * VTP + (ch >> 1) * 32 + (ch & 1) * 8; }
;     const bf16_t* vtbase = vtg + kt0;
.LBB0_116:
	v_mul_f32_e32 v55, 0x3fb8aa3b, v53
	s_mov_b32 s8, 0x3fb8aa3b
	v_fma_f32 v56, v53, s8, -v55
	v_fmac_f32_e32 v56, 0x32a5705f, v53
	v_rndne_f32_e32 v53, v55
	v_sub_f32_e32 v55, v55, v53
	v_add_f32_e32 v55, v55, v56
	v_mul_f32_e32 v56, 0x3fb8aa3b, v54
	v_fma_f32 v57, v54, s8, -v56
	v_fmac_f32_e32 v57, 0x32a5705f, v54
	v_rndne_f32_e32 v54, v56
	v_exp_f32_e32 v55, v55
	v_cvt_i32_f32_e32 v53, v53
	v_sub_f32_e32 v56, v56, v54
	v_add_f32_e32 v56, v56, v57
	v_exp_f32_e32 v56, v56
	v_cvt_i32_f32_e32 v54, v54
	v_ldexp_f32 v53, v55, v53
	v_cndmask_b32_e64 v53, 0, v53, s[40:41]
	v_mov_b32_e32 v55, 0x7f800000
	v_cndmask_b32_e64 v167, v55, v53, s[42:43]
	v_ldexp_f32 v53, v56, v54
	v_cndmask_b32_e64 v53, 0, v53, s[0:1]
	s_lshl_b32 s0, s51, 7
	s_and_b32 s0, s0, 0x2000
	s_lshl_b32 s1, s57, 7
	v_cndmask_b32_e64 v168, v55, v53, s[4:5]
	s_add_i32 s4, s0, s1
	s_or_b32 s4, s4, s58
	v_mul_u32_u24_e32 v53, 0x90, v52
	v_add_lshl_u32 v52, s4, v52, 2
	v_sub_u32_e32 v52, v32, v52
	s_or_b32 s1, s58, s1
	v_add3_u32 v101, 0, v53, v32
	v_add_u32_e32 v102, 0, v52
	s_add_i32 s1, s1, s0
	v_mov_b64_e32 v[98:99], v[50:51]
	v_mov_b64_e32 v[82:83], v[50:51]
	v_mov_b64_e32 v[66:67], v[50:51]
	s_add_i32 s8, s4, 0xffffff81
	s_sub_i32 s12, 33, s1
	s_mov_b32 s13, 0
	v_mov_b64_e32 v[96:97], v[48:49]
	v_mov_b64_e32 v[94:95], v[46:47]
	v_mov_b64_e32 v[92:93], v[44:45]
	v_mov_b64_e32 v[90:91], v[42:43]
	v_mov_b64_e32 v[88:89], v[40:41]
	v_mov_b64_e32 v[86:87], v[38:39]
	v_mov_b64_e32 v[84:85], v[36:37]
	v_mov_b64_e32 v[80:81], v[48:49]
	v_mov_b64_e32 v[78:79], v[46:47]
	v_mov_b64_e32 v[76:77], v[44:45]
	v_mov_b64_e32 v[74:75], v[42:43]
	v_mov_b64_e32 v[72:73], v[40:41]
	v_mov_b64_e32 v[70:71], v[38:39]
	v_mov_b64_e32 v[68:69], v[36:37]
	v_mov_b64_e32 v[64:65], v[48:49]
	v_mov_b64_e32 v[62:63], v[46:47]
	v_mov_b64_e32 v[60:61], v[44:45]
	v_mov_b64_e32 v[58:59], v[42:43]
	v_mov_b64_e32 v[56:57], v[40:41]
	v_mov_b64_e32 v[54:55], v[38:39]
	v_mov_b64_e32 v[52:53], v[36:37]
	v_mov_b64_e32 v[218:219], 0
	v_mov_b64_e32 v[220:221], 0
	v_mov_b64_e32 v[222:223], 0
	v_mov_b64_e32 v[224:225], 0
	v_mov_b64_e32 v[248:249], 0
	v_mov_b64_e32 v[250:251], 0
	v_mov_b64_e32 v[236:237], 0
	v_mov_b64_e32 v[238:239], 0
	v_mov_b64_e32 v[244:245], 0
	v_mov_b64_e32 v[246:247], 0
	s_waitcnt vmcnt(2)
	v_readfirstlane_b32 s98, v228
	s_lshr_b32 s98, s98, 6
	s_lshl_b32 s98, s98, 11
	v_lshrrev_b32_e32 v140, 4, v228
	v_mul_u32_u24_e32 v140, 0xf00, v140
	v_and_b32_e32 v141, 15, v228
	v_lshl_add_u32 v140, v141, 3, v140
	v_sub_u32_e32 v140, v196, v140
	s_nop 0
	v_readfirstlane_b32 s99, v140
	s_lshl_b32 s99, s99, 1
	s_add_i32 s99, s99, 0xf0000
	v_and_b32_e32 v140, 63, v228
	v_lshrrev_b32_e32 v141, 6, v228
	v_lshl_add_u32 v140, v141, 7, v140
	v_add_u32_e32 v141, 64, v140
	v_and_b32_e32 v142, 63, v228
	v_add_u32_e32 v142, 0x400, v142
	v_mul_u32_u24_e32 v132, 0xf10, v140
	v_mul_u32_u24_e32 v133, 0xf10, v141
	v_mul_u32_u24_e32 v134, 0xf10, v142
	v_lshrrev_b32_e32 v132, 16, v132
	v_lshrrev_b32_e32 v133, 16, v133
	v_lshrrev_b32_e32 v134, 16, v134
	v_mul_u32_u24_e32 v135, 17, v132
	v_sub_u32_e32 v140, v140, v135
	v_mul_u32_u24_e32 v135, 17, v133
	v_sub_u32_e32 v141, v141, v135
	v_mul_u32_u24_e32 v135, 17, v134
	v_sub_u32_e32 v142, v142, v135
	v_cmp_eq_u32_e32 vcc, 16, v140
	s_nop 1
	v_cndmask_b32_e64 v140, v140, 0, vcc
	v_cmp_eq_u32_e32 vcc, 16, v141
	s_nop 1
	v_cndmask_b32_e64 v141, v141, 0, vcc
	v_cmp_eq_u32_e32 vcc, 16, v142
	s_nop 1
	v_cndmask_b32_e64 v142, v142, 0, vcc
	v_mul_u32_u24_e32 v132, 0x1e00, v132
	v_mul_u32_u24_e32 v133, 0x1e00, v133
	v_mul_u32_u24_e32 v134, 0x1e00, v134
	v_lshl_add_u32 v132, v140, 4, v132
	v_lshl_add_u32 v133, v141, 4, v133
	v_lshl_add_u32 v134, v142, 4, v134
	v_readfirstlane_b32 s100, v228
	s_lshr_b32 s100, s100, 8
	s_cmp_eq_u32 s100, 0
	s_cbranch_scc1 .Lattn_prio_skip
	s_setprio 1

; #define LAS __attribute__((address_space(3)))
; template <int MODE, bool FROZEN = false>
; __device__ __forceinline__ bool attn_unit(LAS unsigned char* lds, const Params& p, int l, int ua, int ub) {
;     ...
;         if (t + 2 < NT) {
; #pragma unroll
;             for (int i = 0; i < NKC; ++i) *(LAS u32x4*)(lds + kdst[i] + (t & 1) * KBUF) = kr[i];
;         }
;         if (t + 1 < NT) {
; #pragma unroll
;             for (int i = 0; i < NVC; ++i) { *(LAS u32x2*)(lds + vdst[i] + ((t + 1) & 1) * VBUF) = (u32x2){vr[i].x, vr[i].y}; *(LAS u32x2*)(lds + vdst[i] + ((t + 1) & 1) * VBUF + 16) = (u32x2){vr[i].z, vr[i].w}; }
;         }
;         {
;             const size_t advk = (size_t)min(t + 3, NT - 1) * 64 * NPROJ, advv = (size_t)min(t + 2, NT - 1) * 64;
; #pragma unroll
;             for (int i = 0; i < NKC; ++i) kr[i] = *(const u32x4*)(kvbase + advk + ksrc[i]);
; #pragma unroll
;             for (int i = 0; i < NVC; ++i) vr[i] = *(const u32x4*)(vtbase + advv + vsrc[i]);
;         }
;         f32x16 sA0 = sB0, sA1 = sB1;
;         const float c2 = cbB - m_run;
;         const LAS unsigned char* Vb = lds + OFF_V + (t & 1) * VBUF + vlane_off;
;         const LAS unsigned char* Kb = lds + OFF_K + ((t + 1) & 1) * KBUF + klane_off;
;     ...
;         bf16x8 kf0[4], kf1[4], va[NB], vb[NB], pf0, pf1; float ps0, ps1, ps2, ps3;
;         VLOAD(0, va);
;         EXPCVT(0, pf0, ps0);
;         SBAR_();
;         VLOAD(1, vb); PVMMA(va, pf0); EXPCVT(1, pf1, ps1); _Pragma("unroll") for (int g_ = 0; g_ < NB; ++g_) { __builtin_amdgcn_sched_group_barrier(0x008, 1, 0); __builtin_amdgcn_sched_group_barrier(0x100, 1, 0); __builtin_amdgcn_sched_group_barrier(0x400, 8 / NB, 0); __builtin_amdgcn_sched_group_barrier(0x002, 12 / NB, 0); } SBAR_();
;         VLOAD(2, va);
; #pragma unroll
;         for (int d0 = 0; d0 < 4; ++d0) { kf0[d0] = *(const LAS bf16x8*)(Kb + d0 * 32); kf1[d0] = *(const LAS bf16x8*)(Kb + 32 * KPB + d0 * 32); }
;         PVMMA(vb, pf1); EXPCVT(2, pf0, ps2); _Pragma("unroll") for (int g_ = 0; g_ < NB; ++g_) { __builtin_amdgcn_sched_group_barrier(0x008, 1, 0); __builtin_amdgcn_sched_group_barrier(0x100, 1, 0); __builtin_amdgcn_sched_group_barrier(0x400, 8 / NB, 0); __builtin_amdgcn_sched_group_barrier(0x002, 12 / NB, 0); } SBAR_();
;         {
;             f32x16 z0, z1;
; #pragma unroll
;             for (int r = 0; r < 16; ++r) { z0[r] = 0.f; z1[r] = 0.f; }
; #pragma unroll
.LBB0_117:
.LBB0_118:
	s_add_i32 s14, s4, 1
	s_bitcmp1_b32 s14, 0
	s_cselect_b32 s15, 0x4400, 0
	s_cselect_b32 s100, 0, 0x4800
	v_add_u32_e32 v194, s100, v101
	s_sub_i32 s5, 0x4400, s15
	s_min_i32 s10, s4, 0xfd
	s_mul_i32 s10, s10, 0x78000
	s_add_u32 s10, s34, s10
	s_addc_u32 s11, s35, 0
	s_add_u32 s10, s10, s99
	s_addc_u32 s11, s11, 0
	ds_read_b128 v[112:115], v194 offset:34816
	ds_read_b128 v[170:173], v194 offset:39424
	ds_read_b128 v[174:177], v194 offset:44032
	ds_read_b128 v[178:181], v194 offset:48640
	v_exp_f32_e32 v103, v16
	v_exp_f32_e32 v104, v17
	v_mfma_f32_32x32x16_bf16 v[52:67], v[236:239], v[244:247], v[52:67]
	v_exp_f32_e32 v105, v18
	v_exp_f32_e32 v106, v19
	v_cvt_pk_bf16_f32 v16, v103, v104
	v_mfma_f32_32x32x16_bf16 v[36:51], v[218:221], v[244:247], v[36:51]
	s_add_i32 m0, s5, s98
	s_nop 0
	global_load_lds_dwordx4 v132, s[10:11]
	v_exp_f32_e32 v107, v20
	v_exp_f32_e32 v108, v21
	v_cvt_pk_bf16_f32 v17, v105, v106
	v_mfma_f32_32x32x16_bf16 v[84:99], v[222:225], v[244:247], v[84:99]
	s_add_i32 m0, m0, 0x400
	s_nop 0
	global_load_lds_dwordx4 v133, s[10:11]
	v_exp_f32_e32 v109, v22
	v_exp_f32_e32 v110, v23
	v_cvt_pk_bf16_f32 v18, v107, v108
	v_mfma_f32_32x32x16_bf16 v[68:83], v[248:251], v[244:247], v[68:83]
	s_cmp_lg_u32 s98, 0
	s_cbranch_scc1 .Lkdma_skip
	s_add_i32 m0, s5, 0x4000
	s_nop 0
	global_load_lds_dwordx4 v134, s[10:11]
.Lkdma_skip:
	v_add_u32_e32 v195, s15, v166
	v_cvt_pk_bf16_f32 v19, v109, v110
	s_waitcnt lgkmcnt(3)
	s_nop 0
	v_mfma_f32_32x32x16_bf16 v[36:51], v[112:115], v[16:19], v[36:51]
	ds_read_b128 v[20:23], v194 offset:34848
	ds_read_b128 v[218:221], v195 offset:32
	v_exp_f32_e32 v111, v24
	v_exp_f32_e32 v112, v25
	s_nop 0
	v_cvt_pk_bf16_f32 v24, v111, v112
	s_waitcnt lgkmcnt(4)
	v_mfma_f32_32x32x16_bf16 v[84:99], v[170:173], v[16:19], v[84:99]
	ds_read_b128 v[182:185], v194 offset:39456
	ds_read_b128 v[222:225], v195 offset:64
	v_exp_f32_e32 v113, v26
	v_exp_f32_e32 v114, v27
	s_nop 0
	v_cvt_pk_bf16_f32 v25, v113, v114
	s_waitcnt lgkmcnt(5)
	v_mfma_f32_32x32x16_bf16 v[68:83], v[174:177], v[16:19], v[68:83]
	ds_read_b128 v[186:189], v194 offset:44064
	ds_read_b128 v[248:251], v195 offset:96
	v_exp_f32_e32 v115, v28
	v_exp_f32_e32 v170, v29
	s_nop 0
	v_cvt_pk_bf16_f32 v26, v115, v170
	s_waitcnt lgkmcnt(6)
	v_mfma_f32_32x32x16_bf16 v[52:67], v[178:181], v[16:19], v[52:67]
	ds_read_b128 v[16:19], v194 offset:48672
	v_exp_f32_e32 v171, v30
	v_exp_f32_e32 v172, v31
	s_nop 0
	v_cvt_pk_bf16_f32 v27, v171, v172
	s_waitcnt lgkmcnt(6)
	s_nop 0
	v_mfma_f32_32x32x16_bf16 v[36:51], v[20:23], v[24:27], v[36:51]
	ds_read_b128 v[190:193], v194 offset:34880
	ds_read_b128 v[20:23], v195 offset:8736
	v_exp_f32_e32 v173, v0
	v_exp_f32_e32 v174, v1
	s_nop 0
	v_cvt_pk_bf16_f32 v202, v173, v174
	s_waitcnt lgkmcnt(6)
	v_mfma_f32_32x32x16_bf16 v[84:99], v[182:185], v[24:27], v[84:99]
	ds_read_b128 v[206:209], v194 offset:39488
	v_exp_f32_e32 v175, v2
	v_exp_f32_e32 v176, v3
	s_nop 0
	v_cvt_pk_bf16_f32 v203, v175, v176
	s_waitcnt lgkmcnt(5)
	v_mfma_f32_32x32x16_bf16 v[68:83], v[186:189], v[24:27], v[68:83]
	ds_read_b128 v[210:213], v194 offset:44096
	v_exp_f32_e32 v177, v4
	v_exp_f32_e32 v178, v5
	s_nop 0
	v_cvt_pk_bf16_f32 v204, v177, v178
	s_waitcnt lgkmcnt(4)
	v_mfma_f32_32x32x16_bf16 v[52:67], v[16:19], v[24:27], v[52:67]
	ds_read_b128 v[214:217], v194 offset:48704
	ds_read_b128 v[236:239], v194 offset:48736
	ds_read_b128 v[0:3], v195 offset:8704
	v_exp_f32_e32 v179, v6
	v_exp_f32_e32 v180, v7
	s_nop 0
	v_cvt_pk_bf16_f32 v205, v179, v180
	v_exp_f32_e32 v181, v8
	v_exp_f32_e32 v182, v9
	s_waitcnt lgkmcnt(6)
	v_mfma_f32_32x32x16_bf16 v[36:51], v[190:193], v[202:205], v[36:51]
	ds_read_b128 v[24:27], v195 offset:8768
	v_exp_f32_e32 v183, v10
	v_exp_f32_e32 v184, v11
	v_cvt_pk_bf16_f32 v244, v181, v182
	s_waitcnt lgkmcnt(5)
	v_mfma_f32_32x32x16_bf16 v[84:99], v[206:209], v[202:205], v[84:99]
	ds_read_b128 v[28:31], v195 offset:8800
	v_exp_f32_e32 v185, v12
	v_exp_f32_e32 v186, v13
	v_cvt_pk_bf16_f32 v245, v183, v184
	s_sub_i32 s101, 0xd000, s100
	s_waitcnt lgkmcnt(5)
	v_mfma_f32_32x32x16_bf16 v[68:83], v[210:213], v[202:205], v[68:83]
	ds_read_b128 v[16:19], v195
	v_exp_f32_e32 v187, v14
	v_exp_f32_e32 v188, v15
	v_cvt_pk_bf16_f32 v246, v185, v186
	v_add_u32_e32 v192, s101, v158
	s_waitcnt lgkmcnt(5)
	v_mfma_f32_32x32x16_bf16 v[52:67], v[214:217], v[202:205], v[52:67]
	v_add_u32_e32 v193, s101, v160
	v_cvt_pk_bf16_f32 v247, v187, v188
	s_waitcnt lgkmcnt(3)
	v_mfma_f32_32x32x16_bf16 v[0:15], v[0:3], v[116:119], 0
	s_waitcnt vmcnt(3)
	ds_write2_b64 v192, v[136:137], v[138:139] offset1:2
	v_add_f32_e32 v105, v105, v106
	v_add_f32_e32 v106, v107, v108
	v_add_f32_e32 v107, v109, v110
	v_add_f32_e32 v103, v103, v104
	v_mfma_f32_32x32x16_bf16 v[0:15], v[20:23], v[120:123], v[0:15]
	v_add_f32_e32 v106, v106, v107
	v_add_f32_e32 v103, v103, v105
	v_add_f32_e32 v105, v115, v170
	v_add_f32_e32 v107, v171, v172
	s_min_i32 s4, s4, 0xfd
	s_lshl_b32 s4, s4, 7
	s_add_u32 s4, s6, s4
	s_addc_u32 s5, s7, 0
	s_waitcnt lgkmcnt(3)
	v_mfma_f32_32x32x16_bf16 v[0:15], v[24:27], v[124:127], v[0:15]
	s_waitcnt vmcnt(2)
	ds_write2_b64 v193, v[144:145], v[146:147] offset1:2
	v_add_f32_e32 v104, v113, v114
	v_add_f32_e32 v105, v105, v107
	v_add_f32_e32 v107, v111, v112
	v_add_f32_e32 v104, v107, v104
	v_lshl_add_u64 v[206:207], v[154:155], 1, s[4:5]
	s_waitcnt lgkmcnt(3)
	v_mfma_f32_32x32x16_bf16 v[0:15], v[28:31], v[128:131], v[0:15]
	v_add_f32_e32 v107, v177, v178
	v_add_f32_e32 v108, v179, v180
	v_add_f32_e32 v104, v104, v105
	v_add_f32_e32 v105, v175, v176
	v_lshl_add_u64 v[208:209], v[156:157], 1, s[4:5]
	s_waitcnt lgkmcnt(2)
	v_mfma_f32_32x32x16_bf16 v[16:31], v[16:19], v[116:119], 0
	v_add_f32_e32 v107, v107, v108
	v_add_f32_e32 v108, v173, v174
	v_add_f32_e32 v105, v108, v105
	v_add_f32_e32 v105, v105, v107
	s_cmpk_gt_i32 s12, 0x7f
	s_cselect_b64 s[0:1], -1, 0
	s_cmpk_gt_i32 s8, 0x7f
	s_cselect_b64 s[4:5], -1, 0
	s_or_b64 s[10:11], s[0:1], s[4:5]
	v_mfma_f32_32x32x16_bf16 v[16:31], v[218:221], v[120:123], v[16:31]
	ds_read_b128 v[218:221], v194 offset:34912
	v_add_f32_e32 v107, v185, v186
	v_add_f32_e32 v108, v187, v188
	v_add_f32_e32 v103, v103, v106
	v_add_f32_e32 v106, v183, v184
	s_and_b64 vcc, exec, s[10:11]
	v_mfma_f32_32x32x16_bf16 v[16:31], v[222:225], v[124:127], v[16:31]
	ds_read_b128 v[222:225], v194 offset:39520
	global_load_dwordx4 v[136:139], v[206:207], off offset:256
	v_add_f32_e32 v107, v107, v108
	v_add_f32_e32 v108, v181, v182
	v_add_f32_e32 v106, v108, v106
	v_add_f32_e32 v106, v106, v107
	v_mfma_f32_32x32x16_bf16 v[16:31], v[248:251], v[128:131], v[16:31]
	ds_read_b128 v[248:251], v194 offset:44128
	global_load_dwordx4 v[144:147], v[208:209], off offset:256
	v_add_f32_e32 v103, v103, v104
	v_add_f32_e32 v104, v105, v106
	v_add_f32_e32 v103, v103, v104
	v_add_f32_e32 v100, v100, v103
	s_cbranch_vccnz .LBB0_120
	v_add_u32_e32 v189, s13, v102
	v_add_u32_e32 v190, 0x11c80, v189
	v_add_u32_e32 v192, 0x11c88, v189
	v_add_u32_e32 v194, 0x11ca0, v189
	v_add_u32_e32 v202, 0x11ca8, v189
	ds_read2_b32 v[190:191], v190 offset1:1
	ds_read2_b32 v[192:193], v192 offset1:1
	ds_read2_b32 v[194:195], v194 offset1:1
	ds_read2_b32 v[202:203], v202 offset1:1
	v_add_u32_e32 v204, 0x11cc0, v189
	v_add_u32_e32 v206, 0x11cc8, v189
	v_add_u32_e32 v208, 0x11ce0, v189
	v_add_u32_e32 v210, 0x11ce8, v189
	ds_read2_b32 v[204:205], v204 offset1:1
	ds_read2_b32 v[206:207], v206 offset1:1
	ds_read2_b32 v[208:209], v208 offset1:1
	ds_read2_b32 v[210:211], v210 offset1:1
	s_waitcnt lgkmcnt(7)
	v_sub_f32_e32 v191, v191, v169
	v_sub_f32_e32 v190, v190, v169
	s_waitcnt lgkmcnt(2)
	v_sub_f32_e32 v207, v207, v169
	v_sub_f32_e32 v205, v205, v169
	v_sub_f32_e32 v204, v204, v169
	v_sub_f32_e32 v206, v206, v169
	s_waitcnt lgkmcnt(1)
	v_sub_f32_e32 v209, v209, v169
	v_sub_f32_e32 v208, v208, v169
	s_waitcnt lgkmcnt(0)
	v_sub_f32_e32 v211, v211, v169
	v_sub_f32_e32 v210, v210, v169
	v_sub_f32_e32 v193, v193, v169
	v_sub_f32_e32 v192, v192, v169
	v_sub_f32_e32 v195, v195, v169
	v_sub_f32_e32 v194, v194, v169
	v_sub_f32_e32 v203, v203, v169
	v_sub_f32_e32 v202, v202, v169
	v_pk_add_f32 v[22:23], v[22:23], v[202:203]
	v_pk_add_f32 v[20:21], v[20:21], v[194:195]
	v_pk_add_f32 v[18:19], v[18:19], v[192:193]
	v_pk_add_f32 v[16:17], v[16:17], v[190:191]
	v_pk_add_f32 v[30:31], v[30:31], v[210:211]
	v_pk_add_f32 v[28:29], v[28:29], v[208:209]
	v_pk_add_f32 v[26:27], v[26:27], v[206:207]
	v_pk_add_f32 v[24:25], v[24:25], v[204:205]
	v_add_u32_e32 v190, 0x11d00, v189
	v_add_u32_e32 v192, 0x11d08, v189
	v_add_u32_e32 v194, 0x11d20, v189
	v_add_u32_e32 v202, 0x11d28, v189
	ds_read2_b32 v[190:191], v190 offset1:1
	ds_read2_b32 v[192:193], v192 offset1:1
	ds_read2_b32 v[194:195], v194 offset1:1
	ds_read2_b32 v[202:203], v202 offset1:1
	v_add_u32_e32 v204, 0x11d40, v189
	v_add_u32_e32 v206, 0x11d48, v189
	v_add_u32_e32 v208, 0x11d60, v189
	ds_read2_b32 v[204:205], v204 offset1:1
	v_add_u32_e32 v189, 0x11d68, v189
	ds_read2_b32 v[206:207], v206 offset1:1
	ds_read2_b32 v[208:209], v208 offset1:1
	ds_read2_b32 v[210:211], v189 offset1:1
	s_waitcnt lgkmcnt(7)
	v_sub_f32_e32 v191, v191, v169
	v_sub_f32_e32 v190, v190, v169
	s_waitcnt lgkmcnt(3)
	v_sub_f32_e32 v205, v205, v169
	v_sub_f32_e32 v204, v204, v169
	s_waitcnt lgkmcnt(2)
	v_sub_f32_e32 v207, v207, v169
	v_sub_f32_e32 v206, v206, v169
	s_waitcnt lgkmcnt(1)
	v_sub_f32_e32 v209, v209, v169
	v_sub_f32_e32 v208, v208, v169
	s_waitcnt lgkmcnt(0)
	v_sub_f32_e32 v211, v211, v169
	v_sub_f32_e32 v210, v210, v169
	v_sub_f32_e32 v193, v193, v169
	v_sub_f32_e32 v192, v192, v169
	v_sub_f32_e32 v195, v195, v169
	v_sub_f32_e32 v194, v194, v169
	v_sub_f32_e32 v203, v203, v169
	v_sub_f32_e32 v202, v202, v169
	v_pk_add_f32 v[6:7], v[6:7], v[202:203]
	v_pk_add_f32 v[4:5], v[4:5], v[194:195]
	v_pk_add_f32 v[2:3], v[2:3], v[192:193]
	v_pk_add_f32 v[0:1], v[0:1], v[190:191]
	v_pk_add_f32 v[14:15], v[14:15], v[210:211]
	v_pk_add_f32 v[12:13], v[12:13], v[208:209]
	v_pk_add_f32 v[10:11], v[10:11], v[206:207]
	v_pk_add_f32 v[8:9], v[8:9], v[204:205]

; template <int MODE, bool FROZEN = false>
; __device__ __forceinline__ bool attn_unit(LAS unsigned char* lds, const Params& p, int l, int ua, int ub) {
;     ...
;         if (t + 1 < NT) { ATT_BIAS(t + 1, tmr); ATT_UPD(tmr); }
;         asm volatile("s_waitcnt lgkmcnt(0)" ::: "memory"); __builtin_amdgcn_s_barrier(); asm volatile("" ::: "memory");
.LBB0_123:
	s_waitcnt vmcnt(2) lgkmcnt(0)
	s_barrier
	s_addk_i32 s13, 0x100
	s_sub_i32 s8, s8, 64
	s_add_i32 s12, s12, 64
	s_cmpk_eq_u32 s13, 0xff00
	s_cbranch_scc1 .LBB0_125
	s_mov_b32 s4, s14
	s_branch .LBB0_118
